# P11c: rows prefetched two ahead (loop unrolled x2, two raw-input register sets): twice the row bytes in flight per wave
# baseline (speedup 1.0000x reference)
; DI void phase11c(const Params& P) {
;     ...
;   h8 nx0, nx1, na0, na1;
;   {
;     const int tt = t0 < NTOK ? t0 : 0;
;     nx0 = *reinterpret_cast<const h8*>(h1h + (long)tt * 1024 + lane * 16); nx1 = *reinterpret_cast<const h8*>(h1h + (long)tt * 1024 + lane * 16 + 8);
;     na0 = *reinterpret_cast<const h8*>(Zp + (long)tt * 1024 + lane * 16); na1 = *reinterpret_cast<const h8*>(Zp + (long)tt * 1024 + lane * 16 + 8);
;   }
;   for (int t = t0; t < NTOK; t += tstep) {
;     const h8 x0 = nx0, x1 = nx1, a0 = na0, a1 = na1;
;     {
;       const int tn = t + tstep < NTOK ? t + tstep : t;
;       nx0 = *reinterpret_cast<const h8*>(h1h + (long)tn * 1024 + lane * 16); nx1 = *reinterpret_cast<const h8*>(h1h + (long)tn * 1024 + lane * 16 + 8);
;       na0 = *reinterpret_cast<const h8*>(Zp + (long)tn * 1024 + lane * 16); na1 = *reinterpret_cast<const h8*>(Zp + (long)tn * 1024 + lane * 16 + 8);
;     }
;     float z[16]; float s = 0.f;
; #pragma unroll
;     for (int k = 0; k < 8; ++k) { z[k] = (float)a0[k] + ALPHA * (float)x0[k]; z[8 + k] = (float)a1[k] + ALPHA * (float)x1[k]; }
.LBB0_1634:
	s_or_b64 exec, exec, s[0:1]
	v_readlane_b32 s2, v254, 39
	v_readlane_b32 s3, v254, 40
	s_waitcnt lgkmcnt(0)
	s_barrier
	s_and_saveexec_b64 s[0:1], s[2:3]
	s_cbranch_execz .LBB0_1637
	v_and_b32_e32 v32, 0x3f0, v209
	v_readlane_b32 s0, v254, 0
	v_mov_b32_e32 v33, v32
	v_readlane_b32 s4, v254, 4
	v_readlane_b32 s5, v254, 5
	v_readlane_b32 s6, v254, 6
	v_readlane_b32 s7, v254, 7
	s_nop 2
	global_load_dwordx4 v[0:3], v33, s[4:5] offset:3072
	s_nop 0
	global_load_dwordx4 v[4:7], v33, s[6:7] offset:3072
	global_load_dwordx4 v[8:11], v33, s[4:5] offset:2048
	global_load_dwordx4 v[12:15], v33, s[6:7] offset:2048
	global_load_dwordx4 v[16:19], v33, s[4:5] offset:1024
	global_load_dwordx4 v[20:23], v33, s[6:7] offset:1024
	global_load_dwordx4 v[24:27], v33, s[4:5]
	global_load_dwordx4 v[28:31], v33, s[6:7]
	v_readlane_b32 s1, v254, 1
	s_add_u32 s0, s78, 0xa000000
	s_addc_u32 s1, s79, 0
	v_lshrrev_b32_e32 v50, 1, v32
	v_lshlrev_b64 v[32:33], 11, v[210:211]
	v_mov_b32_e32 v51, 0
	v_lshl_add_u64 v[34:35], s[0:1], 0, v[32:33]
	v_lshl_add_u64 v[32:33], s[54:55], 0, v[32:33]
	v_lshl_add_u64 v[34:35], v[34:35], 0, v[50:51]
	v_lshl_add_u64 v[48:49], v[32:33], 0, v[50:51]
	global_load_dwordx2 v[36:37], v[34:35], off offset:1024
	global_load_dwordx2 v[38:39], v[34:35], off offset:1536
	global_load_dwordx2 v[44:45], v[34:35], off
	global_load_dwordx2 v[46:47], v[34:35], off offset:512
	s_nop 0
	global_load_dwordx2 v[32:33], v[48:49], off offset:1024
	global_load_dwordx2 v[34:35], v[48:49], off offset:1536
	global_load_dwordx2 v[40:41], v[48:49], off
	global_load_dwordx2 v[42:43], v[48:49], off offset:512
	v_readlane_b32 s2, v254, 2
	v_readlane_b32 s3, v254, 3
	s_lshl_b32 s2, s64, 3
	v_lshlrev_b64 v[52:53], 12, v[210:211]
	v_lshl_or_b32 v52, v208, 4, v52
	s_ashr_i32 s3, s2, 31
	v_lshl_add_u64 v[48:49], s[54:55], 0, v[50:51]
	v_lshl_add_u64 v[50:51], s[0:1], 0, v[50:51]
	v_lshl_add_u64 v[52:53], s[76:77], 0, v[52:53]
	s_lshl_b64 s[4:5], s[2:3], 12
	s_mov_b64 s[6:7], 0
	s_movk_i32 s3, 0x7fff
	s_mov_b32 s9, 0x8000
	s_mov_b32 s8, 0x3f9837f0
	v_mov_b32_e32 v54, 0x3727c5ac
	s_mov_b32 s10, 0x800000
	v_add_u32_e32 v112, s2, v210
	v_cmp_gt_i32_e64 s[0:1], s9, v112
	s_nop 1
	v_cndmask_b32_e64 v112, v210, v112, s[0:1]
	v_ashrrev_i32_e32 v113, 31, v112
	v_lshlrev_b64 v[112:113], 11, v[112:113]
	v_lshl_add_u64 v[114:115], v[48:49], 0, v[112:113]
	v_lshl_add_u64 v[112:113], v[50:51], 0, v[112:113]
	global_load_dwordx2 v[104:105], v[114:115], off
	global_load_dwordx2 v[106:107], v[114:115], off offset:512
	global_load_dwordx2 v[96:97], v[114:115], off offset:1024
	global_load_dwordx2 v[98:99], v[114:115], off offset:1536
	global_load_dwordx2 v[108:109], v[112:113], off
	global_load_dwordx2 v[110:111], v[112:113], off offset:512
	global_load_dwordx2 v[100:101], v[112:113], off offset:1024
	global_load_dwordx2 v[102:103], v[112:113], off offset:1536
	s_waitcnt vmcnt(0)
.LBB0_1636:
	v_add_u32_e32 v55, s2, v210
	v_add_u32_e32 v112, s2, v55
	v_cmp_gt_i32_e64 s[0:1], s9, v112
	s_waitcnt vmcnt(16)
	v_cvt_f32_f16_sdwa v57, v44 dst_sel:DWORD dst_unused:UNUSED_PAD src0_sel:WORD_1
	v_cvt_f32_f16_e32 v56, v44
	v_cvt_f32_f16_sdwa v59, v40 dst_sel:DWORD dst_unused:UNUSED_PAD src0_sel:WORD_1
	v_cvt_f32_f16_e32 v58, v40
	v_cvt_f32_f16_sdwa v61, v45 dst_sel:DWORD dst_unused:UNUSED_PAD src0_sel:WORD_1
	v_cvt_f32_f16_e32 v60, v45
	v_cvt_f32_f16_sdwa v45, v41 dst_sel:DWORD dst_unused:UNUSED_PAD src0_sel:WORD_1
	v_cvt_f32_f16_e32 v44, v41
	v_cvt_f32_f16_sdwa v41, v46 dst_sel:DWORD dst_unused:UNUSED_PAD src0_sel:WORD_1
	v_cvt_f32_f16_e32 v40, v46
	v_cvt_f32_f16_sdwa v63, v42 dst_sel:DWORD dst_unused:UNUSED_PAD src0_sel:WORD_1
	v_cvt_f32_f16_e32 v62, v42
	v_cvt_f32_f16_sdwa v65, v47 dst_sel:DWORD dst_unused:UNUSED_PAD src0_sel:WORD_1
	v_cvt_f32_f16_e32 v64, v47
	v_cvt_f32_f16_sdwa v47, v43 dst_sel:DWORD dst_unused:UNUSED_PAD src0_sel:WORD_1
	v_cvt_f32_f16_e32 v46, v43
	v_cvt_f32_f16_sdwa v43, v36 dst_sel:DWORD dst_unused:UNUSED_PAD src0_sel:WORD_1
	v_cvt_f32_f16_e32 v42, v36
	v_cvt_f32_f16_sdwa v67, v32 dst_sel:DWORD dst_unused:UNUSED_PAD src0_sel:WORD_1
	v_cvt_f32_f16_e32 v66, v32
	v_cvt_f32_f16_sdwa v69, v37 dst_sel:DWORD dst_unused:UNUSED_PAD src0_sel:WORD_1
	v_cvt_f32_f16_e32 v68, v37
	v_cvt_f32_f16_sdwa v37, v33 dst_sel:DWORD dst_unused:UNUSED_PAD src0_sel:WORD_1
	v_cvt_f32_f16_e32 v36, v33
	v_cvt_f32_f16_sdwa v33, v38 dst_sel:DWORD dst_unused:UNUSED_PAD src0_sel:WORD_1
	v_cvt_f32_f16_e32 v32, v38
	v_cvt_f32_f16_sdwa v71, v34 dst_sel:DWORD dst_unused:UNUSED_PAD src0_sel:WORD_1
	v_cvt_f32_f16_e32 v70, v34
	v_cvt_f32_f16_sdwa v73, v39 dst_sel:DWORD dst_unused:UNUSED_PAD src0_sel:WORD_1
	v_cvt_f32_f16_e32 v72, v39
	v_cvt_f32_f16_sdwa v39, v35 dst_sel:DWORD dst_unused:UNUSED_PAD src0_sel:WORD_1
	v_cvt_f32_f16_e32 v38, v35
	v_cndmask_b32_e64 v34, v210, v112, s[0:1]
	v_ashrrev_i32_e32 v35, 31, v34
	v_lshlrev_b64 v[34:35], 11, v[34:35]
	v_lshl_add_u64 v[74:75], v[48:49], 0, v[34:35]
	v_lshl_add_u64 v[76:77], v[50:51], 0, v[34:35]
	v_pk_fma_f32 v[56:57], v[58:59], s[8:9], v[56:57] op_sel_hi:[1,0,1]
	v_pk_fma_f32 v[58:59], v[44:45], s[8:9], v[60:61] op_sel_hi:[1,0,1]
	v_pk_fma_f32 v[60:61], v[62:63], s[8:9], v[40:41] op_sel_hi:[1,0,1]
	v_pk_fma_f32 v[62:63], v[46:47], s[8:9], v[64:65] op_sel_hi:[1,0,1]
	v_pk_fma_f32 v[64:65], v[66:67], s[8:9], v[42:43] op_sel_hi:[1,0,1]
	v_pk_fma_f32 v[66:67], v[36:37], s[8:9], v[68:69] op_sel_hi:[1,0,1]
	v_pk_fma_f32 v[68:69], v[70:71], s[8:9], v[32:33] op_sel_hi:[1,0,1]
	v_pk_fma_f32 v[70:71], v[38:39], s[8:9], v[72:73] op_sel_hi:[1,0,1]
	global_load_dwordx2 v[40:41], v[74:75], off
	global_load_dwordx2 v[42:43], v[74:75], off offset:512
; DI float wave_sum(float v) { v = dpp_row_sum_f0(v); return (rl_f(v, 0) + rl_f(v, 16)) + (rl_f(v, 32) + rl_f(v, 48)); }
; DI void phase11c(const Params& P) {
;     ...
;     for (int k = 0; k < 8; ++k) { z[k] = (float)a0[k] + ALPHA * (float)x0[k]; z[8 + k] = (float)a1[k] + ALPHA * (float)x1[k]; }
; #pragma unroll
;     for (int k = 0; k < 16; ++k) s += z[k];
;     const float mu = wave_sum(s) * (1.f / 1024.f);
;     float q = 0.f;
; #pragma unroll
;     for (int k = 0; k < 16; ++k) { const float d = z[k] - mu; q += d * d; }
;     const float rstd = rsqrtf(wave_sum(q) * (1.f / 1024.f) + 1e-5f);
; #pragma unroll
;     for (int k = 0; k < 4; ++k) {
;       float4 o;
;       o.x = (z[4 * k] - mu) * rstd * gg[k].x + bb[k].x; o.y = (z[4 * k + 1] - mu) * rstd * gg[k].y + bb[k].y;
;       o.z = (z[4 * k + 2] - mu) * rstd * gg[k].z + bb[k].z; o.w = (z[4 * k + 3] - mu) * rstd * gg[k].w + bb[k].w;
;       *reinterpret_cast<float4*>(P.out + (long)t * 1024 + lane * 16 + k * 4) = o;
;     }
;   }
	global_load_dwordx2 v[32:33], v[74:75], off offset:1024
	global_load_dwordx2 v[34:35], v[74:75], off offset:1536
	global_load_dwordx2 v[44:45], v[76:77], off
	global_load_dwordx2 v[46:47], v[76:77], off offset:512
	global_load_dwordx2 v[36:37], v[76:77], off offset:1024
	global_load_dwordx2 v[38:39], v[76:77], off offset:1536
	v_cmp_lt_i32_e32 vcc, s3, v55
	v_mov_b32_e32 v210, v55
	v_add_f32_e32 v55, 0, v56
	v_add_f32_e32 v55, v57, v55
	v_add_f32_e32 v55, v58, v55
	v_add_f32_e32 v55, v59, v55
	v_add_f32_e32 v55, v60, v55
	v_add_f32_e32 v55, v61, v55
	v_add_f32_e32 v55, v62, v55
	v_add_f32_e32 v55, v63, v55
	v_add_f32_e32 v55, v64, v55
	v_add_f32_e32 v55, v65, v55
	v_add_f32_e32 v55, v66, v55
	v_add_f32_e32 v55, v67, v55
	v_add_f32_e32 v55, v68, v55
	v_add_f32_e32 v55, v69, v55
	v_add_f32_e32 v55, v70, v55
	v_add_f32_e32 v55, v71, v55
	s_or_b64 s[6:7], vcc, s[6:7]
	s_nop 0
	v_add_f32_dpp v55, v55, v55 quad_perm:[1,0,3,2] row_mask:0xf bank_mask:0xf bound_ctrl:1
	s_nop 1
	v_add_f32_dpp v55, v55, v55 quad_perm:[2,3,0,1] row_mask:0xf bank_mask:0xf bound_ctrl:1
	s_nop 1
	v_add_f32_dpp v55, v55, v55 row_half_mirror row_mask:0xf bank_mask:0xf bound_ctrl:1
	s_nop 1
	v_add_f32_dpp v55, v55, v55 row_mirror row_mask:0xf bank_mask:0xf bound_ctrl:1
	s_nop 0
	v_readlane_b32 s11, v55, 16
	v_readlane_b32 s12, v55, 48
	v_readlane_b32 s0, v55, 0
	v_readlane_b32 s1, v55, 32
	v_mov_b32_e32 v72, s11
	v_mov_b32_e32 v73, s12
	v_pk_add_f32 v[72:73], s[0:1], v[72:73]
	s_nop 0
	v_add_f32_e32 v55, v72, v73
	v_mul_f32_e32 v72, 0x3a800000, v55
	v_pk_add_f32 v[56:57], v[56:57], v[72:73] op_sel_hi:[1,0] neg_lo:[0,1] neg_hi:[0,1]
	v_pk_add_f32 v[58:59], v[58:59], v[72:73] op_sel_hi:[1,0] neg_lo:[0,1] neg_hi:[0,1]
	v_pk_add_f32 v[60:61], v[60:61], v[72:73] op_sel_hi:[1,0] neg_lo:[0,1] neg_hi:[0,1]
	v_pk_add_f32 v[62:63], v[62:63], v[72:73] op_sel_hi:[1,0] neg_lo:[0,1] neg_hi:[0,1]
	v_pk_add_f32 v[64:65], v[64:65], v[72:73] op_sel_hi:[1,0] neg_lo:[0,1] neg_hi:[0,1]
	v_pk_add_f32 v[66:67], v[66:67], v[72:73] op_sel_hi:[1,0] neg_lo:[0,1] neg_hi:[0,1]
	v_pk_add_f32 v[68:69], v[68:69], v[72:73] op_sel_hi:[1,0] neg_lo:[0,1] neg_hi:[0,1]
	v_pk_add_f32 v[70:71], v[70:71], v[72:73] op_sel_hi:[1,0] neg_lo:[0,1] neg_hi:[0,1]
	v_pk_mul_f32 v[72:73], v[56:57], v[56:57]
	v_pk_mul_f32 v[74:75], v[58:59], v[58:59]
	v_add_f32_e32 v55, v72, v73
	v_add_f32_e32 v55, v74, v55
	v_pk_mul_f32 v[76:77], v[60:61], v[60:61]
	v_add_f32_e32 v55, v75, v55
	v_add_f32_e32 v55, v76, v55
	v_pk_mul_f32 v[78:79], v[62:63], v[62:63]
	v_add_f32_e32 v55, v77, v55
	v_add_f32_e32 v55, v78, v55
	v_pk_mul_f32 v[80:81], v[64:65], v[64:65]
	v_add_f32_e32 v55, v79, v55
	v_add_f32_e32 v55, v80, v55
	v_pk_mul_f32 v[82:83], v[66:67], v[66:67]
	v_add_f32_e32 v55, v81, v55
	v_add_f32_e32 v55, v82, v55
	v_pk_mul_f32 v[84:85], v[68:69], v[68:69]
	v_add_f32_e32 v55, v83, v55
	v_add_f32_e32 v55, v84, v55
	v_pk_mul_f32 v[86:87], v[70:71], v[70:71]
	v_add_f32_e32 v55, v85, v55
	v_add_f32_e32 v55, v86, v55
	v_add_f32_e32 v55, v87, v55
	s_nop 1
	v_add_f32_dpp v55, v55, v55 quad_perm:[1,0,3,2] row_mask:0xf bank_mask:0xf bound_ctrl:1
	s_nop 1
	v_add_f32_dpp v55, v55, v55 quad_perm:[2,3,0,1] row_mask:0xf bank_mask:0xf bound_ctrl:1
	s_nop 1
	v_add_f32_dpp v55, v55, v55 row_half_mirror row_mask:0xf bank_mask:0xf bound_ctrl:1
	s_nop 1
	v_add_f32_dpp v55, v55, v55 row_mirror row_mask:0xf bank_mask:0xf bound_ctrl:1
	s_nop 0
	v_readlane_b32 s11, v55, 16
	v_readlane_b32 s12, v55, 48
	v_readlane_b32 s0, v55, 0
	v_readlane_b32 s1, v55, 32
	v_mov_b32_e32 v72, s11
	v_mov_b32_e32 v73, s12
	v_pk_add_f32 v[72:73], s[0:1], v[72:73]
	s_nop 0
	v_add_f32_e32 v55, v72, v73
	v_fmamk_f32 v55, v55, 0x3a800000, v54
	v_mul_f32_e32 v72, 0x4b800000, v55
	v_cmp_gt_f32_e32 vcc, s10, v55
	s_nop 1
	v_cndmask_b32_e32 v55, v55, v72, vcc
	v_rsq_f32_e32 v55, v55
	s_nop 0
	v_mul_f32_e32 v72, 0x45800000, v55
	v_cndmask_b32_e32 v72, v55, v72, vcc
	v_pk_mul_f32 v[56:57], v[56:57], v[72:73] op_sel_hi:[1,0]
	v_pk_mul_f32 v[58:59], v[58:59], v[72:73] op_sel_hi:[1,0]
	v_pk_mul_f32 v[60:61], v[60:61], v[72:73] op_sel_hi:[1,0]
	v_pk_mul_f32 v[62:63], v[62:63], v[72:73] op_sel_hi:[1,0]
	v_pk_mul_f32 v[64:65], v[64:65], v[72:73] op_sel_hi:[1,0]
	v_pk_mul_f32 v[66:67], v[66:67], v[72:73] op_sel_hi:[1,0]
	v_pk_mul_f32 v[68:69], v[68:69], v[72:73] op_sel_hi:[1,0]
	v_pk_mul_f32 v[70:71], v[70:71], v[72:73] op_sel_hi:[1,0]
	v_pk_fma_f32 v[56:57], v[24:25], v[56:57], v[28:29]
	v_pk_fma_f32 v[58:59], v[26:27], v[58:59], v[30:31]
	v_pk_fma_f32 v[60:61], v[16:17], v[60:61], v[20:21]
	v_pk_fma_f32 v[62:63], v[18:19], v[62:63], v[22:23]
	v_pk_fma_f32 v[64:65], v[8:9], v[64:65], v[12:13]
	v_pk_fma_f32 v[66:67], v[10:11], v[66:67], v[14:15]
	v_pk_fma_f32 v[68:69], v[0:1], v[68:69], v[4:5]
	v_pk_fma_f32 v[70:71], v[2:3], v[70:71], v[6:7]
	global_store_dwordx4 v[52:53], v[56:59], off
	global_store_dwordx4 v[52:53], v[60:63], off offset:1024
	global_store_dwordx4 v[52:53], v[64:67], off offset:2048
	global_store_dwordx4 v[52:53], v[68:71], off offset:3072
	v_lshl_add_u64 v[52:53], v[52:53], 0, s[4:5]
	s_andn2_b64 exec, exec, s[6:7]
	s_cbranch_execz .LBB0_1637
; DI float wave_sum(float v) { v = dpp_row_sum_f0(v); return (rl_f(v, 0) + rl_f(v, 16)) + (rl_f(v, 32) + rl_f(v, 48)); }
; DI void phase11c(const Params& P) {
;     ...
;   for (int t = t0; t < NTOK; t += tstep) {
;     const h8 x0 = nx0, x1 = nx1, a0 = na0, a1 = na1;
;     {
;       const int tn = t + tstep < NTOK ? t + tstep : t;
;       nx0 = *reinterpret_cast<const h8*>(h1h + (long)tn * 1024 + lane * 16); nx1 = *reinterpret_cast<const h8*>(h1h + (long)tn * 1024 + lane * 16 + 8);
;       na0 = *reinterpret_cast<const h8*>(Zp + (long)tn * 1024 + lane * 16); na1 = *reinterpret_cast<const h8*>(Zp + (long)tn * 1024 + lane * 16 + 8);
;     }
;     float z[16]; float s = 0.f;
; #pragma unroll
;     for (int k = 0; k < 8; ++k) { z[k] = (float)a0[k] + ALPHA * (float)x0[k]; z[8 + k] = (float)a1[k] + ALPHA * (float)x1[k]; }
; #pragma unroll
;     for (int k = 0; k < 16; ++k) s += z[k];
;     const float mu = wave_sum(s) * (1.f / 1024.f);
	v_add_u32_e32 v55, s2, v210
	v_add_u32_e32 v112, s2, v55
	v_cmp_gt_i32_e64 s[0:1], s9, v112
	s_waitcnt vmcnt(16)
	v_cvt_f32_f16_sdwa v57, v108 dst_sel:DWORD dst_unused:UNUSED_PAD src0_sel:WORD_1
	v_cvt_f32_f16_e32 v56, v108
	v_cvt_f32_f16_sdwa v59, v104 dst_sel:DWORD dst_unused:UNUSED_PAD src0_sel:WORD_1
	v_cvt_f32_f16_e32 v58, v104
	v_cvt_f32_f16_sdwa v61, v109 dst_sel:DWORD dst_unused:UNUSED_PAD src0_sel:WORD_1
	v_cvt_f32_f16_e32 v60, v109
	v_cvt_f32_f16_sdwa v109, v105 dst_sel:DWORD dst_unused:UNUSED_PAD src0_sel:WORD_1
	v_cvt_f32_f16_e32 v108, v105
	v_cvt_f32_f16_sdwa v105, v110 dst_sel:DWORD dst_unused:UNUSED_PAD src0_sel:WORD_1
	v_cvt_f32_f16_e32 v104, v110
	v_cvt_f32_f16_sdwa v63, v106 dst_sel:DWORD dst_unused:UNUSED_PAD src0_sel:WORD_1
	v_cvt_f32_f16_e32 v62, v106
	v_cvt_f32_f16_sdwa v65, v111 dst_sel:DWORD dst_unused:UNUSED_PAD src0_sel:WORD_1
	v_cvt_f32_f16_e32 v64, v111
	v_cvt_f32_f16_sdwa v111, v107 dst_sel:DWORD dst_unused:UNUSED_PAD src0_sel:WORD_1
	v_cvt_f32_f16_e32 v110, v107
	v_cvt_f32_f16_sdwa v107, v100 dst_sel:DWORD dst_unused:UNUSED_PAD src0_sel:WORD_1
	v_cvt_f32_f16_e32 v106, v100
	v_cvt_f32_f16_sdwa v67, v96 dst_sel:DWORD dst_unused:UNUSED_PAD src0_sel:WORD_1
	v_cvt_f32_f16_e32 v66, v96
	v_cvt_f32_f16_sdwa v69, v101 dst_sel:DWORD dst_unused:UNUSED_PAD src0_sel:WORD_1
	v_cvt_f32_f16_e32 v68, v101
	v_cvt_f32_f16_sdwa v101, v97 dst_sel:DWORD dst_unused:UNUSED_PAD src0_sel:WORD_1
	v_cvt_f32_f16_e32 v100, v97
	v_cvt_f32_f16_sdwa v97, v102 dst_sel:DWORD dst_unused:UNUSED_PAD src0_sel:WORD_1
	v_cvt_f32_f16_e32 v96, v102
	v_cvt_f32_f16_sdwa v71, v98 dst_sel:DWORD dst_unused:UNUSED_PAD src0_sel:WORD_1
	v_cvt_f32_f16_e32 v70, v98
	v_cvt_f32_f16_sdwa v73, v103 dst_sel:DWORD dst_unused:UNUSED_PAD src0_sel:WORD_1
	v_cvt_f32_f16_e32 v72, v103
	v_cvt_f32_f16_sdwa v103, v99 dst_sel:DWORD dst_unused:UNUSED_PAD src0_sel:WORD_1
	v_cvt_f32_f16_e32 v102, v99
	v_cndmask_b32_e64 v98, v210, v112, s[0:1]
	v_ashrrev_i32_e32 v99, 31, v98
	v_lshlrev_b64 v[98:99], 11, v[98:99]
	v_lshl_add_u64 v[74:75], v[48:49], 0, v[98:99]
	v_lshl_add_u64 v[76:77], v[50:51], 0, v[98:99]
	v_pk_fma_f32 v[56:57], v[58:59], s[8:9], v[56:57] op_sel_hi:[1,0,1]
	v_pk_fma_f32 v[58:59], v[108:109], s[8:9], v[60:61] op_sel_hi:[1,0,1]
	v_pk_fma_f32 v[60:61], v[62:63], s[8:9], v[104:105] op_sel_hi:[1,0,1]
	v_pk_fma_f32 v[62:63], v[110:111], s[8:9], v[64:65] op_sel_hi:[1,0,1]
	v_pk_fma_f32 v[64:65], v[66:67], s[8:9], v[106:107] op_sel_hi:[1,0,1]
	v_pk_fma_f32 v[66:67], v[100:101], s[8:9], v[68:69] op_sel_hi:[1,0,1]
	v_pk_fma_f32 v[68:69], v[70:71], s[8:9], v[96:97] op_sel_hi:[1,0,1]
	v_pk_fma_f32 v[70:71], v[102:103], s[8:9], v[72:73] op_sel_hi:[1,0,1]
	global_load_dwordx2 v[104:105], v[74:75], off
	global_load_dwordx2 v[106:107], v[74:75], off offset:512
	global_load_dwordx2 v[96:97], v[74:75], off offset:1024
	global_load_dwordx2 v[98:99], v[74:75], off offset:1536
	global_load_dwordx2 v[108:109], v[76:77], off
	global_load_dwordx2 v[110:111], v[76:77], off offset:512
	global_load_dwordx2 v[100:101], v[76:77], off offset:1024
	global_load_dwordx2 v[102:103], v[76:77], off offset:1536
	v_cmp_lt_i32_e32 vcc, s3, v55
	v_mov_b32_e32 v210, v55
	v_add_f32_e32 v55, 0, v56
	v_add_f32_e32 v55, v57, v55
	v_add_f32_e32 v55, v58, v55
	v_add_f32_e32 v55, v59, v55
	v_add_f32_e32 v55, v60, v55
	v_add_f32_e32 v55, v61, v55
	v_add_f32_e32 v55, v62, v55
	v_add_f32_e32 v55, v63, v55
	v_add_f32_e32 v55, v64, v55
	v_add_f32_e32 v55, v65, v55
	v_add_f32_e32 v55, v66, v55
	v_add_f32_e32 v55, v67, v55
	v_add_f32_e32 v55, v68, v55
	v_add_f32_e32 v55, v69, v55
	v_add_f32_e32 v55, v70, v55
	v_add_f32_e32 v55, v71, v55
	s_or_b64 s[6:7], vcc, s[6:7]
	s_nop 0
	v_add_f32_dpp v55, v55, v55 quad_perm:[1,0,3,2] row_mask:0xf bank_mask:0xf bound_ctrl:1
	s_nop 1
	v_add_f32_dpp v55, v55, v55 quad_perm:[2,3,0,1] row_mask:0xf bank_mask:0xf bound_ctrl:1
	s_nop 1
	v_add_f32_dpp v55, v55, v55 row_half_mirror row_mask:0xf bank_mask:0xf bound_ctrl:1
; DI float wave_sum(float v) { v = dpp_row_sum_f0(v); return (rl_f(v, 0) + rl_f(v, 16)) + (rl_f(v, 32) + rl_f(v, 48)); }
; DI void phase11c(const Params& P) {
;     ...
;     const float mu = wave_sum(s) * (1.f / 1024.f);
;     float q = 0.f;
; #pragma unroll
;     for (int k = 0; k < 16; ++k) { const float d = z[k] - mu; q += d * d; }
;     const float rstd = rsqrtf(wave_sum(q) * (1.f / 1024.f) + 1e-5f);
; #pragma unroll
;     for (int k = 0; k < 4; ++k) {
;       float4 o;
;       o.x = (z[4 * k] - mu) * rstd * gg[k].x + bb[k].x; o.y = (z[4 * k + 1] - mu) * rstd * gg[k].y + bb[k].y;
;       o.z = (z[4 * k + 2] - mu) * rstd * gg[k].z + bb[k].z; o.w = (z[4 * k + 3] - mu) * rstd * gg[k].w + bb[k].w;
;       *reinterpret_cast<float4*>(P.out + (long)t * 1024 + lane * 16 + k * 4) = o;
;     }
;   }
	s_nop 1
	v_add_f32_dpp v55, v55, v55 row_mirror row_mask:0xf bank_mask:0xf bound_ctrl:1
	s_nop 0
	v_readlane_b32 s11, v55, 16
	v_readlane_b32 s12, v55, 48
	v_readlane_b32 s0, v55, 0
	v_readlane_b32 s1, v55, 32
	v_mov_b32_e32 v72, s11
	v_mov_b32_e32 v73, s12
	v_pk_add_f32 v[72:73], s[0:1], v[72:73]
	s_nop 0
	v_add_f32_e32 v55, v72, v73
	v_mul_f32_e32 v72, 0x3a800000, v55
	v_pk_add_f32 v[56:57], v[56:57], v[72:73] op_sel_hi:[1,0] neg_lo:[0,1] neg_hi:[0,1]
	v_pk_add_f32 v[58:59], v[58:59], v[72:73] op_sel_hi:[1,0] neg_lo:[0,1] neg_hi:[0,1]
	v_pk_add_f32 v[60:61], v[60:61], v[72:73] op_sel_hi:[1,0] neg_lo:[0,1] neg_hi:[0,1]
	v_pk_add_f32 v[62:63], v[62:63], v[72:73] op_sel_hi:[1,0] neg_lo:[0,1] neg_hi:[0,1]
	v_pk_add_f32 v[64:65], v[64:65], v[72:73] op_sel_hi:[1,0] neg_lo:[0,1] neg_hi:[0,1]
	v_pk_add_f32 v[66:67], v[66:67], v[72:73] op_sel_hi:[1,0] neg_lo:[0,1] neg_hi:[0,1]
	v_pk_add_f32 v[68:69], v[68:69], v[72:73] op_sel_hi:[1,0] neg_lo:[0,1] neg_hi:[0,1]
	v_pk_add_f32 v[70:71], v[70:71], v[72:73] op_sel_hi:[1,0] neg_lo:[0,1] neg_hi:[0,1]
	v_pk_mul_f32 v[72:73], v[56:57], v[56:57]
	v_pk_mul_f32 v[74:75], v[58:59], v[58:59]
	v_add_f32_e32 v55, v72, v73
	v_add_f32_e32 v55, v74, v55
	v_pk_mul_f32 v[76:77], v[60:61], v[60:61]
	v_add_f32_e32 v55, v75, v55
	v_add_f32_e32 v55, v76, v55
	v_pk_mul_f32 v[78:79], v[62:63], v[62:63]
	v_add_f32_e32 v55, v77, v55
	v_add_f32_e32 v55, v78, v55
	v_pk_mul_f32 v[80:81], v[64:65], v[64:65]
	v_add_f32_e32 v55, v79, v55
	v_add_f32_e32 v55, v80, v55
	v_pk_mul_f32 v[82:83], v[66:67], v[66:67]
	v_add_f32_e32 v55, v81, v55
	v_add_f32_e32 v55, v82, v55
	v_pk_mul_f32 v[84:85], v[68:69], v[68:69]
	v_add_f32_e32 v55, v83, v55
	v_add_f32_e32 v55, v84, v55
	v_pk_mul_f32 v[86:87], v[70:71], v[70:71]
	v_add_f32_e32 v55, v85, v55
	v_add_f32_e32 v55, v86, v55
	v_add_f32_e32 v55, v87, v55
	s_nop 1
	v_add_f32_dpp v55, v55, v55 quad_perm:[1,0,3,2] row_mask:0xf bank_mask:0xf bound_ctrl:1
	s_nop 1
	v_add_f32_dpp v55, v55, v55 quad_perm:[2,3,0,1] row_mask:0xf bank_mask:0xf bound_ctrl:1
	s_nop 1
	v_add_f32_dpp v55, v55, v55 row_half_mirror row_mask:0xf bank_mask:0xf bound_ctrl:1
	s_nop 1
	v_add_f32_dpp v55, v55, v55 row_mirror row_mask:0xf bank_mask:0xf bound_ctrl:1
	s_nop 0
	v_readlane_b32 s11, v55, 16
	v_readlane_b32 s12, v55, 48
	v_readlane_b32 s0, v55, 0
	v_readlane_b32 s1, v55, 32
	v_mov_b32_e32 v72, s11
	v_mov_b32_e32 v73, s12
	v_pk_add_f32 v[72:73], s[0:1], v[72:73]
	s_nop 0
	v_add_f32_e32 v55, v72, v73
	v_fmamk_f32 v55, v55, 0x3a800000, v54
	v_mul_f32_e32 v72, 0x4b800000, v55
	v_cmp_gt_f32_e32 vcc, s10, v55
	s_nop 1
	v_cndmask_b32_e32 v55, v55, v72, vcc
	v_rsq_f32_e32 v55, v55
	s_nop 0
	v_mul_f32_e32 v72, 0x45800000, v55
	v_cndmask_b32_e32 v72, v55, v72, vcc
	v_pk_mul_f32 v[56:57], v[56:57], v[72:73] op_sel_hi:[1,0]
	v_pk_mul_f32 v[58:59], v[58:59], v[72:73] op_sel_hi:[1,0]
	v_pk_mul_f32 v[60:61], v[60:61], v[72:73] op_sel_hi:[1,0]
	v_pk_mul_f32 v[62:63], v[62:63], v[72:73] op_sel_hi:[1,0]
	v_pk_mul_f32 v[64:65], v[64:65], v[72:73] op_sel_hi:[1,0]
	v_pk_mul_f32 v[66:67], v[66:67], v[72:73] op_sel_hi:[1,0]
	v_pk_mul_f32 v[68:69], v[68:69], v[72:73] op_sel_hi:[1,0]
	v_pk_mul_f32 v[70:71], v[70:71], v[72:73] op_sel_hi:[1,0]
	v_pk_fma_f32 v[56:57], v[24:25], v[56:57], v[28:29]
	v_pk_fma_f32 v[58:59], v[26:27], v[58:59], v[30:31]
	v_pk_fma_f32 v[60:61], v[16:17], v[60:61], v[20:21]
	v_pk_fma_f32 v[62:63], v[18:19], v[62:63], v[22:23]
	v_pk_fma_f32 v[64:65], v[8:9], v[64:65], v[12:13]
	v_pk_fma_f32 v[66:67], v[10:11], v[66:67], v[14:15]
	v_pk_fma_f32 v[68:69], v[0:1], v[68:69], v[4:5]
	v_pk_fma_f32 v[70:71], v[2:3], v[70:71], v[6:7]
	global_store_dwordx4 v[52:53], v[56:59], off
	global_store_dwordx4 v[52:53], v[60:63], off offset:1024
	global_store_dwordx4 v[52:53], v[64:67], off offset:2048
	global_store_dwordx4 v[52:53], v[68:71], off offset:3072
	v_lshl_add_u64 v[52:53], v[52:53], 0, s[4:5]
	s_andn2_b64 exec, exec, s[6:7]
	s_cbranch_execnz .LBB0_1636
